# NSA selected-branch unmasked pair body hand-scheduled: K/V fragment LDS reads of both tiles prefetched, QK of both tiles ahead of softmax; nfv 256
# speedup vs baseline: 1.0010x; 1.0010x over previous
.LBB0_1046:
	s_andn2_b64 vcc, exec, s[22:23]
	s_cbranch_vccnz .LBB0_1048
	s_sub_i32 s22, s81, 64
	s_and_b32 s22, s22, 0xc0
	s_mulk_i32 s22, 0xa0
	v_add_u32_e32 v193, s22, v153
	ds_read_b128 v[194:197], v193
	ds_read_b128 v[198:201], v193 offset:64
	ds_read_b128 v[202:205], v193 offset:2560
	ds_read_b128 v[206:209], v193 offset:2624
	ds_read_b128 v[210:213], v193 offset:5120
	ds_read_b128 v[214:217], v193 offset:5184
	ds_read_b128 v[218:221], v193 offset:7680
	s_waitcnt lgkmcnt(14)
	v_mfma_f32_16x16x32_bf16 v[0:3], v[88:91], v[60:63], 0
	ds_read_b128 v[222:225], v193 offset:7744
	s_waitcnt lgkmcnt(13)
	v_mfma_f32_16x16x32_bf16 v[4:7], v[96:99], v[60:63], 0
	s_waitcnt lgkmcnt(11)
	v_mfma_f32_16x16x32_bf16 v[8:11], v[104:107], v[60:63], 0
	s_waitcnt lgkmcnt(9)
	v_mfma_f32_16x16x32_bf16 v[12:15], v[112:115], v[60:63], 0
	v_mfma_f32_16x16x32_bf16 v[0:3], v[92:95], v[56:59], v[0:3]
	v_mfma_f32_16x16x32_bf16 v[4:7], v[100:103], v[56:59], v[4:7]
	v_mfma_f32_16x16x32_bf16 v[8:11], v[108:111], v[56:59], v[8:11]
	s_waitcnt lgkmcnt(8)
	v_mfma_f32_16x16x32_bf16 v[12:15], v[116:119], v[56:59], v[12:15]
	s_waitcnt lgkmcnt(7)
	v_mfma_f32_16x16x32_bf16 v[240:243], v[194:197], v[60:63], 0
	ds_read_b128 v[88:91], v143 offset:40960
	ds_read_b128 v[92:95], v143 offset:43520
	s_waitcnt lgkmcnt(7)
	v_mfma_f32_16x16x32_bf16 v[244:247], v[202:205], v[60:63], 0
	ds_read_b128 v[96:99], v143 offset:46080
	ds_read_b128 v[100:103], v143 offset:48640
	s_waitcnt lgkmcnt(7)
	v_mfma_f32_16x16x32_bf16 v[248:251], v[210:213], v[60:63], 0
	ds_read_b128 v[104:107], v143 offset:41024
	ds_read_b128 v[108:111], v143 offset:43584
	s_waitcnt lgkmcnt(7)
	v_mfma_f32_16x16x32_bf16 v[252:255], v[218:221], v[60:63], 0
	ds_read_b128 v[112:115], v143 offset:46144
	ds_read_b128 v[116:119], v143 offset:48704
	v_mfma_f32_16x16x32_bf16 v[240:243], v[198:201], v[56:59], v[240:243]
	v_mfma_f32_16x16x32_bf16 v[244:247], v[206:209], v[56:59], v[244:247]
	v_mfma_f32_16x16x32_bf16 v[248:251], v[214:217], v[56:59], v[248:251]
	s_waitcnt lgkmcnt(8)
	v_mfma_f32_16x16x32_bf16 v[252:255], v[222:225], v[56:59], v[252:255]
	s_setprio 0
	ds_read_b128 v[194:197], v193 offset:40960
	ds_read_b128 v[198:201], v193 offset:43520
	ds_read_b128 v[202:205], v193 offset:46080
	ds_read_b128 v[206:209], v193 offset:48640
	ds_read_b128 v[210:213], v193 offset:41024
	ds_read_b128 v[214:217], v193 offset:43584
	ds_read_b128 v[218:221], v193 offset:46144
	v_mul_f32_e64 v226, -v146, v147
	v_cndmask_b32_e64 v226, v179, v226, s[20:21]
	v_add_f32_e32 v227, v192, v226
	v_add_f32_e32 v228, v146, v227
	v_add_f32_e32 v229, v137, v227
	v_add_f32_e32 v230, v188, v227
	v_fmamk_f32 v0, v0, 0x3e38aa3b, v227
	v_fmamk_f32 v1, v1, 0x3e38aa3b, v228
	v_fmamk_f32 v2, v2, 0x3e38aa3b, v229
	v_fmamk_f32 v3, v3, 0x3e38aa3b, v230
	v_exp_f32_e32 v0, v0
	v_exp_f32_e32 v1, v1
	v_exp_f32_e32 v2, v2
	v_exp_f32_e32 v3, v3
	v_add_f32_e32 v227, v189, v226
	v_add_f32_e32 v228, v146, v227
	v_add_f32_e32 v229, v137, v227
	v_add_f32_e32 v230, v188, v227
	v_fmamk_f32 v4, v4, 0x3e38aa3b, v227
	v_fmamk_f32 v5, v5, 0x3e38aa3b, v228
	v_fmamk_f32 v6, v6, 0x3e38aa3b, v229
	v_fmamk_f32 v7, v7, 0x3e38aa3b, v230
	v_exp_f32_e32 v4, v4
	v_exp_f32_e32 v5, v5
	v_exp_f32_e32 v6, v6
	v_exp_f32_e32 v7, v7
	v_add_f32_e32 v227, v190, v226
	v_add_f32_e32 v228, v146, v227
	v_add_f32_e32 v229, v137, v227
	v_add_f32_e32 v230, v188, v227
	v_fmamk_f32 v8, v8, 0x3e38aa3b, v227
	v_fmamk_f32 v9, v9, 0x3e38aa3b, v228
	v_fmamk_f32 v10, v10, 0x3e38aa3b, v229
	v_fmamk_f32 v11, v11, 0x3e38aa3b, v230
	v_exp_f32_e32 v8, v8
	v_exp_f32_e32 v9, v9
	v_exp_f32_e32 v10, v10
	v_exp_f32_e32 v11, v11
	v_add_f32_e32 v227, v191, v226
	v_add_f32_e32 v228, v146, v227
	v_add_f32_e32 v229, v137, v227
	v_add_f32_e32 v230, v188, v227
	v_fmamk_f32 v12, v12, 0x3e38aa3b, v227
	v_fmamk_f32 v13, v13, 0x3e38aa3b, v228
	v_fmamk_f32 v14, v14, 0x3e38aa3b, v229
	v_fmamk_f32 v15, v15, 0x3e38aa3b, v230
	v_exp_f32_e32 v12, v12
	v_exp_f32_e32 v13, v13
	v_exp_f32_e32 v14, v14
	v_exp_f32_e32 v15, v15
	v_cvt_pk_bf16_f32 v226, v0, v1
	v_cvt_pk_bf16_f32 v227, v2, v3
	v_cvt_pk_bf16_f32 v228, v4, v5
	v_cvt_pk_bf16_f32 v229, v6, v7
	v_cvt_pk_bf16_f32 v230, v8, v9
	v_cvt_pk_bf16_f32 v231, v10, v11
	v_cvt_pk_bf16_f32 v232, v12, v13
	v_cvt_pk_bf16_f32 v233, v14, v15
	s_nop 1
	s_setprio 1
	s_waitcnt lgkmcnt(14)
	v_mfma_f32_16x16x32_bf16 v[0:3], v[88:91], v[226:229], v[36:39]
	ds_read_b128 v[222:225], v193 offset:48704
	s_waitcnt lgkmcnt(14)
	v_mfma_f32_16x16x32_bf16 v[4:7], v[92:95], v[226:229], v[40:43]
	s_waitcnt lgkmcnt(13)
	v_mfma_f32_16x16x32_bf16 v[8:11], v[96:99], v[226:229], v[44:47]
	s_waitcnt lgkmcnt(12)
	v_mfma_f32_16x16x32_bf16 v[12:15], v[100:103], v[226:229], v[84:87]
	v_mov_b32_e32 v36, s28
	v_mov_b32_e32 v37, s28
	v_mov_b32_e32 v38, s28
	v_mov_b32_e32 v39, s28
	s_nop 1
	v_mfma_f32_16x16x32_bf16 v[80:83], v[36:39], v[226:229], v[32:35]
	s_waitcnt lgkmcnt(11)
	v_mfma_f32_16x16x32_bf16 v[0:3], v[104:107], v[230:233], v[0:3]
	s_waitcnt lgkmcnt(10)
	v_mfma_f32_16x16x32_bf16 v[4:7], v[108:111], v[230:233], v[4:7]
	s_waitcnt lgkmcnt(9)
	v_mfma_f32_16x16x32_bf16 v[8:11], v[112:115], v[230:233], v[8:11]
	s_waitcnt lgkmcnt(8)
	v_mfma_f32_16x16x32_bf16 v[12:15], v[116:119], v[230:233], v[12:15]
	v_mfma_f32_16x16x32_bf16 v[80:83], v[36:39], v[230:233], v[80:83]
	s_setprio 0
	v_mul_f32_e64 v226, -v146, v141
	v_cndmask_b32_e64 v226, v179, v226, s[0:1]
	v_add_f32_e32 v227, v192, v226
	v_add_f32_e32 v228, v146, v227
	v_add_f32_e32 v229, v137, v227
	v_add_f32_e32 v230, v188, v227
	v_fmamk_f32 v240, v240, 0x3e38aa3b, v227
	v_fmamk_f32 v241, v241, 0x3e38aa3b, v228
	v_fmamk_f32 v242, v242, 0x3e38aa3b, v229
	v_fmamk_f32 v243, v243, 0x3e38aa3b, v230
	v_exp_f32_e32 v240, v240
	v_exp_f32_e32 v241, v241
	v_exp_f32_e32 v242, v242
	v_exp_f32_e32 v243, v243
	v_add_f32_e32 v227, v189, v226
	v_add_f32_e32 v228, v146, v227
	v_add_f32_e32 v229, v137, v227
	v_add_f32_e32 v230, v188, v227
	v_fmamk_f32 v244, v244, 0x3e38aa3b, v227
	v_fmamk_f32 v245, v245, 0x3e38aa3b, v228
	v_fmamk_f32 v246, v246, 0x3e38aa3b, v229
	v_fmamk_f32 v247, v247, 0x3e38aa3b, v230
	v_exp_f32_e32 v244, v244
	v_exp_f32_e32 v245, v245
	v_exp_f32_e32 v246, v246
	v_exp_f32_e32 v247, v247
	v_add_f32_e32 v227, v190, v226
	v_add_f32_e32 v228, v146, v227
	v_add_f32_e32 v229, v137, v227
	v_add_f32_e32 v230, v188, v227
	v_fmamk_f32 v248, v248, 0x3e38aa3b, v227
	v_fmamk_f32 v249, v249, 0x3e38aa3b, v228
	v_fmamk_f32 v250, v250, 0x3e38aa3b, v229
	v_fmamk_f32 v251, v251, 0x3e38aa3b, v230
	v_exp_f32_e32 v248, v248
	v_exp_f32_e32 v249, v249
	v_exp_f32_e32 v250, v250
	v_exp_f32_e32 v251, v251
	v_add_f32_e32 v227, v191, v226
	v_add_f32_e32 v228, v146, v227
	v_add_f32_e32 v229, v137, v227
	v_add_f32_e32 v230, v188, v227
	v_fmamk_f32 v252, v252, 0x3e38aa3b, v227
	v_fmamk_f32 v253, v253, 0x3e38aa3b, v228
	v_fmamk_f32 v254, v254, 0x3e38aa3b, v229
	v_fmamk_f32 v255, v255, 0x3e38aa3b, v230
	v_exp_f32_e32 v252, v252
	v_exp_f32_e32 v253, v253
	v_exp_f32_e32 v254, v254
	v_exp_f32_e32 v255, v255
	v_cvt_pk_bf16_f32 v240, v240, v241
	v_cvt_pk_bf16_f32 v241, v242, v243
	v_cvt_pk_bf16_f32 v242, v244, v245
	v_cvt_pk_bf16_f32 v243, v246, v247
	v_cvt_pk_bf16_f32 v248, v248, v249
	v_cvt_pk_bf16_f32 v249, v250, v251
	v_cvt_pk_bf16_f32 v250, v252, v253
	v_cvt_pk_bf16_f32 v251, v254, v255
	s_nop 1
	s_setprio 1
	s_waitcnt lgkmcnt(7)
	v_mfma_f32_16x16x32_bf16 v[0:3], v[194:197], v[240:243], v[0:3]
	s_waitcnt lgkmcnt(6)
	v_mfma_f32_16x16x32_bf16 v[4:7], v[198:201], v[240:243], v[4:7]
	s_waitcnt lgkmcnt(5)
	v_mfma_f32_16x16x32_bf16 v[8:11], v[202:205], v[240:243], v[8:11]
	s_waitcnt lgkmcnt(4)
	v_mfma_f32_16x16x32_bf16 v[12:15], v[206:209], v[240:243], v[12:15]
	v_mfma_f32_16x16x32_bf16 v[80:83], v[36:39], v[240:243], v[80:83]
	s_waitcnt lgkmcnt(3)
	v_mfma_f32_16x16x32_bf16 v[0:3], v[210:213], v[248:251], v[0:3]
	s_waitcnt lgkmcnt(2)
	v_mfma_f32_16x16x32_bf16 v[4:7], v[214:217], v[248:251], v[4:7]
	s_waitcnt lgkmcnt(1)
	v_mfma_f32_16x16x32_bf16 v[8:11], v[218:221], v[248:251], v[8:11]
	s_waitcnt lgkmcnt(0)
	v_mfma_f32_16x16x32_bf16 v[12:15], v[222:225], v[248:251], v[12:15]
	v_mfma_f32_16x16x32_bf16 v[80:83], v[36:39], v[248:251], v[80:83]

	.amdhsa_kernel _Z4mega4Args
		.amdhsa_group_segment_fixed_size 0
		.amdhsa_private_segment_fixed_size 0
		.amdhsa_kernarg_size 432
		.amdhsa_user_sgpr_count 2
		.amdhsa_user_sgpr_dispatch_ptr 0
		.amdhsa_user_sgpr_queue_ptr 0
		.amdhsa_user_sgpr_kernarg_segment_ptr 1
		.amdhsa_user_sgpr_dispatch_id 0
		.amdhsa_user_sgpr_kernarg_preload_length 0
		.amdhsa_user_sgpr_kernarg_preload_offset 0
		.amdhsa_user_sgpr_private_segment_size 0
		.amdhsa_uses_dynamic_stack 0
		.amdhsa_enable_private_segment 0
		.amdhsa_system_sgpr_workgroup_id_x 1
		.amdhsa_system_sgpr_workgroup_id_y 0
		.amdhsa_system_sgpr_workgroup_id_z 0
		.amdhsa_system_sgpr_workgroup_info 0
		.amdhsa_system_vgpr_workitem_id 2
		.amdhsa_next_free_vgpr 256
		.amdhsa_next_free_sgpr 98
		.amdhsa_accum_offset 256
		.amdhsa_reserve_vcc 1
		.amdhsa_float_round_mode_32 0
		.amdhsa_float_round_mode_16_64 0
		.amdhsa_float_denorm_mode_32 3
		.amdhsa_float_denorm_mode_16_64 3
		.amdhsa_dx10_clamp 1
		.amdhsa_ieee_mode 1
		.amdhsa_fp16_overflow 0
		.amdhsa_tg_split 0
		.amdhsa_exception_fp_ieee_invalid_op 0
		.amdhsa_exception_fp_denorm_src 0
		.amdhsa_exception_fp_ieee_div_zero 0
		.amdhsa_exception_fp_ieee_overflow 0
		.amdhsa_exception_fp_ieee_underflow 0
		.amdhsa_exception_fp_ieee_inexact 0
		.amdhsa_exception_int_div_zero 0
	.end_amdhsa_kernel

amdhsa.kernels:
  - .agpr_count:     0
    .args:
      - .offset:         0
        .size:           176
        .value_kind:     by_value
      - .offset:         176
        .size:           4
        .value_kind:     hidden_block_count_x
      - .offset:         180
        .size:           4
        .value_kind:     hidden_block_count_y
      - .offset:         184
        .size:           4
        .value_kind:     hidden_block_count_z
      - .offset:         188
        .size:           2
        .value_kind:     hidden_group_size_x
      - .offset:         190
        .size:           2
        .value_kind:     hidden_group_size_y
      - .offset:         192
        .size:           2
        .value_kind:     hidden_group_size_z
      - .offset:         194
        .size:           2
        .value_kind:     hidden_remainder_x
      - .offset:         196
        .size:           2
        .value_kind:     hidden_remainder_y
      - .offset:         198
        .size:           2
        .value_kind:     hidden_remainder_z
      - .offset:         216
        .size:           8
        .value_kind:     hidden_global_offset_x
      - .offset:         224
        .size:           8
        .value_kind:     hidden_global_offset_y
      - .offset:         232
        .size:           8
        .value_kind:     hidden_global_offset_z
      - .offset:         240
        .size:           2
        .value_kind:     hidden_grid_dims
      - .offset:         264
        .size:           8
        .value_kind:     hidden_multigrid_sync_arg
      - .offset:         296
        .size:           4
        .value_kind:     hidden_dynamic_lds_size
    .group_segment_fixed_size: 0
    .kernarg_segment_align: 8
    .kernarg_segment_size: 432
    .language:       OpenCL C
    .language_version:
      - 2
      - 0
    .max_flat_workgroup_size: 512
    .name:           _Z4mega4Args
    .private_segment_fixed_size: 0
    .sgpr_count:     104
    .sgpr_spill_count: 11
    .symbol:         _Z4mega4Args.kd
    .uniform_work_group_size: 1
    .uses_dynamic_stack: false
    .vgpr_count:     256
    .vgpr_spill_count: 0
    .wavefront_size: 64
